# gate/up GEMM: per-unit accumulator zeroing folded into the SwiGLU epilogue (list-scheduled into its wait-state slots); header zeroes only before the first unit
# baseline (speedup 1.0000x reference)
;     __device__ __forceinline__ void krange(const Unit& u, int nt, int& k0, int& kn) const { if (u.kh >= 0) { kn = nt >> 1; k0 = u.kh * kn; } else { k0 = 0; kn = nt; } }
;     __device__ __forceinline__ void krange(const Unit& u, int nt, int& k0, int& kn) const { if (u.pn < 3) { k0 = 0; kn = 4; } else { k0 = 4; kn = 2; } }
; #define PG8_STAGE(bufoff, gbase, voff) do { _Pragma("unroll") for (int _i = 0; _i < 2; ++_i) \
;         __builtin_amdgcn_global_load_lds((const unsigned*)((const char*)(gbase) + (voff)[_i]), (PG8_LAS unsigned*)(lds + (bufoff) + ldsw + _i * 8192), 16, 0, 0); } while (0)
; #define PG8_LDA(dst, b, h) do { int aoff; asm volatile("v_add_u32 %0, %1, %2" : "=v"(aoff) : "s"(ua), "v"(foff)); _Pragma("unroll") for (int m = 0; m < 4; ++m) _Pragma("unroll") for (int k = 0; k < 2; ++k) dst[m][k] = *(const PG8_LAS bf16x8*)(lds + PG8_SA(b, h) + aoff + m * 2048 + k * 1024); } while (0)
; #define PG8_WAIT_L(n) asm volatile("s_waitcnt lgkmcnt(" #n ")" ::: "memory")
; template <class Epi, class Sched>
; __device__ __forceinline__ void gemm_phase(PG8_LAS unsigned char* lds, const Gemm g, const Sched& S, const Epi& E) {
;     ...
;         int ncnt = nt; size_t nk = 0;
;         if constexpr (Sched::SPLIT) { if (has_next) { int k0_, kn_; S.krange(nxt, nt, k0_, kn_); ncnt = kn_; nk = (size_t)k0_ * kstep; } }
;         const char* nA = has_next ? (const char*)g.A + (size_t)nxt.pm * tstep + nk : cA; const char* nB = has_next ? (const char*)g.Bt + (size_t)nxt.pn * tstep + nk : cB;
;         for (int t = 0; t < cnt; t += 2) {
;             const bool last = (t == cnt - 2);
;             const char* a1 = cA + (size_t)(t + 1) * kstep;
;             const char* a2 = last ? nA : cA + (size_t)(t + 2) * kstep; const char* b2 = last ? nB : cB + (size_t)(t + 2) * kstep;
;             const char* a3 = a2 + kstep; const char* b3 = b2 + kstep;
;             if (last && has_next) S.a_ready(nxt);
;             PG8_LDB(B0, 0, 0); PG8_SCHED; PG8_LDA(At, 0, 0); PG8_STAGE(PG8_SA(1, 1), a1 + hstep, voffA);
;             PG8_WAIT_L(8); PG8_BAR; PG8_WAIT_L(0); PG8_MMA(0, 0, At, B0); PG8_BAR; PG8_SCHED;
;     ...
; #pragma unroll
;         for (int a = 0; a < 2; ++a)
; #pragma unroll
;             for (int b = 0; b < 2; ++b)
; #pragma unroll
;                 for (int m = 0; m < 4; ++m)
; #pragma unroll
;                     for (int n = 0; n < 2; ++n) acc[a][b][m][n] = (f32x4){0.f, 0.f, 0.f, 0.f};
.LBB0_1108:
	v_mov_b64_e32 v[2:3], s[54:55]
	s_ashr_i32 s21, s20, 31
	v_cmp_lt_i64_e32 vcc, s[24:25], v[2:3]
	s_lshl_b64 s[24:25], s[20:21], 19
	s_add_u32 s24, s66, s24
	s_addc_u32 s25, s67, s25
	s_and_b64 s[28:29], vcc, exec
	s_cselect_b32 s5, s25, s27
	s_cselect_b32 s21, s24, s26
	s_ashr_i32 s19, s18, 31
	s_lshl_b64 s[28:29], s[18:19], 19
	s_add_u32 s28, s9, s28
	s_addc_u32 s29, s10, s29
	s_and_b64 s[46:47], vcc, exec
	s_cselect_b32 s19, s29, s45
	s_cselect_b32 s61, s28, s44
	s_add_u32 s26, s26, 0x40080
	s_addc_u32 s27, s27, 0
	s_add_u32 s62, s44, 0x100
	v_mov_b32_e32 v2, 0
	s_addc_u32 s63, s45, 0
	s_mov_b32 s74, -2
	v_mov_b32_e32 v3, v2
	s_cmp_lg_u32 s60, 1
	s_cbranch_scc1 .Lp7_zero_skip
	v_mov_b32_e32 v4, v2
	v_mov_b32_e32 v5, v2
	v_mov_b32_e32 v10, v2
	v_mov_b32_e32 v11, v2
	v_mov_b32_e32 v12, v2
	v_mov_b32_e32 v13, v2
	v_mov_b32_e32 v18, v2
	v_mov_b32_e32 v19, v2
	v_mov_b32_e32 v20, v2
	v_mov_b32_e32 v21, v2
	v_mov_b32_e32 v26, v2
	v_mov_b32_e32 v27, v2
	v_mov_b32_e32 v28, v2
	v_mov_b32_e32 v29, v2
	v_mov_b32_e32 v34, v2
	v_mov_b32_e32 v35, v2
	v_mov_b32_e32 v36, v2
	v_mov_b32_e32 v37, v2
	v_mov_b32_e32 v42, v2
	v_mov_b32_e32 v43, v2
	v_mov_b32_e32 v44, v2
	v_mov_b32_e32 v45, v2
	v_mov_b32_e32 v50, v2
	v_mov_b32_e32 v51, v2
	v_mov_b32_e32 v52, v2
	v_mov_b32_e32 v53, v2
	v_mov_b32_e32 v58, v2
	v_mov_b32_e32 v59, v2
	v_mov_b32_e32 v60, v2
	v_mov_b32_e32 v61, v2
	v_mov_b32_e32 v6, v2
	v_mov_b32_e32 v7, v2
	v_mov_b32_e32 v8, v2
	v_mov_b32_e32 v9, v2
	v_mov_b32_e32 v14, v2
	v_mov_b32_e32 v15, v2
	v_mov_b32_e32 v16, v2
	v_mov_b32_e32 v17, v2
	v_mov_b32_e32 v22, v2
	v_mov_b32_e32 v23, v2
	v_mov_b32_e32 v24, v2
	v_mov_b32_e32 v25, v2
	v_mov_b32_e32 v30, v2
	v_mov_b32_e32 v31, v2
	v_mov_b32_e32 v32, v2
	v_mov_b32_e32 v33, v2
	v_mov_b32_e32 v38, v2
	v_mov_b32_e32 v39, v2
	v_mov_b32_e32 v40, v2
	v_mov_b32_e32 v41, v2
	v_mov_b32_e32 v46, v2
	v_mov_b32_e32 v47, v2
	v_mov_b32_e32 v48, v2
	v_mov_b32_e32 v49, v2
	v_mov_b32_e32 v54, v2
	v_mov_b32_e32 v55, v2
	v_mov_b32_e32 v56, v2
	v_mov_b32_e32 v57, v2
	v_mov_b32_e32 v62, v2
	v_mov_b32_e32 v63, v2
	v_mov_b32_e32 v64, v2
	v_mov_b32_e32 v65, v2
	v_mov_b32_e32 v66, v2
	v_mov_b32_e32 v67, v2
	v_mov_b32_e32 v68, v2
	v_mov_b32_e32 v69, v2
	v_mov_b32_e32 v74, v2
	v_mov_b32_e32 v75, v2
	v_mov_b32_e32 v76, v2
	v_mov_b32_e32 v77, v2
	v_mov_b32_e32 v82, v2
	v_mov_b32_e32 v83, v2
	v_mov_b32_e32 v84, v2
	v_mov_b32_e32 v85, v2
	v_mov_b32_e32 v90, v2
	v_mov_b32_e32 v91, v2
	v_mov_b32_e32 v92, v2
	v_mov_b32_e32 v93, v2
	v_mov_b32_e32 v98, v2
	v_mov_b32_e32 v99, v2
	v_mov_b32_e32 v100, v2
	v_mov_b32_e32 v101, v2
	v_mov_b32_e32 v106, v2
	v_mov_b32_e32 v107, v2
	v_mov_b32_e32 v108, v2
	v_mov_b32_e32 v109, v2
	v_mov_b32_e32 v114, v2
	v_mov_b32_e32 v115, v2
	v_mov_b32_e32 v116, v2
	v_mov_b32_e32 v117, v2
	v_mov_b32_e32 v122, v2
	v_mov_b32_e32 v123, v2
	v_mov_b32_e32 v124, v2
	v_mov_b32_e32 v125, v2
	v_mov_b32_e32 v70, v2
	v_mov_b32_e32 v71, v2
	v_mov_b32_e32 v72, v2
	v_mov_b32_e32 v73, v2
	v_mov_b32_e32 v78, v2
	v_mov_b32_e32 v79, v2
	v_mov_b32_e32 v80, v2
	v_mov_b32_e32 v81, v2
	v_mov_b32_e32 v86, v2
	v_mov_b32_e32 v87, v2
	v_mov_b32_e32 v88, v2
	v_mov_b32_e32 v89, v2
	v_mov_b32_e32 v94, v2
	v_mov_b32_e32 v95, v2
	v_mov_b32_e32 v96, v2
	v_mov_b32_e32 v97, v2
	v_mov_b32_e32 v102, v2
	v_mov_b32_e32 v103, v2
	v_mov_b32_e32 v104, v2
	v_mov_b32_e32 v105, v2
	v_mov_b32_e32 v110, v2
	v_mov_b32_e32 v111, v2
	v_mov_b32_e32 v112, v2
	v_mov_b32_e32 v113, v2
	v_mov_b32_e32 v118, v2
	v_mov_b32_e32 v119, v2
	v_mov_b32_e32 v120, v2
	v_mov_b32_e32 v121, v2
	v_mov_b32_e32 v126, v2
	v_mov_b32_e32 v127, v2
	v_mov_b32_e32 v128, v2
	v_mov_b32_e32 v129, v2
.Lp7_zero_skip:
.LBB0_1109:
	s_add_u32 s44, s26, 0xfffc0080
	s_addc_u32 s45, s27, -1
	s_add_i32 s75, 0, 0x10000
	v_add_u32 v142, s51, v1
	s_cmp_eq_u32 s74, 12
	v_add_u32_e32 v158, s75, v142
	ds_read_b128 v[142:145], v158
	ds_read_b128 v[146:149], v158 offset:1024
	ds_read_b128 v[150:153], v158 offset:2048
	ds_read_b128 v[158:161], v158 offset:3072
	s_cselect_b32 s47, s5, s45
	s_cselect_b32 s46, s21, s44
	s_cselect_b32 s45, s19, s63
	s_cselect_b32 s44, s61, s62
	v_add_u32 v162, s50, v1
	v_lshl_add_u64 v[194:195], s[26:27], 0, v[138:139]
	v_add_u32_e32 v190, 0, v162
	s_add_i32 m0, s3, 0xc000
	ds_read_b128 v[162:165], v190
	ds_read_b128 v[166:169], v190 offset:1024
	ds_read_b128 v[170:173], v190 offset:2048
	ds_read_b128 v[174:177], v190 offset:3072
	ds_read_b128 v[178:181], v190 offset:4096
	ds_read_b128 v[182:185], v190 offset:5120
	ds_read_b128 v[186:189], v190 offset:6144
	ds_read_b128 v[190:193], v190 offset:7168
	global_load_lds_dwordx4 v[194:195], off
	v_lshl_add_u64 v[194:195], s[26:27], 0, v[140:141]
	s_add_i32 m0, s3, 0xe000
	s_nop 0
	global_load_lds_dwordx4 v[194:195], off
	s_waitcnt lgkmcnt(8)
	s_barrier
	s_waitcnt lgkmcnt(0)
	s_setprio 1
	s_waitcnt lgkmcnt(0)
	v_mfma_f32_16x16x32_bf16 v[126:129], v[142:145], v[162:165], v[126:129]
	v_mfma_f32_16x16x32_bf16 v[118:121], v[150:153], v[162:165], v[118:121]
	v_mfma_f32_16x16x32_bf16 v[110:113], v[142:145], v[170:173], v[110:113]
	v_mfma_f32_16x16x32_bf16 v[102:105], v[150:153], v[170:173], v[102:105]
	v_mfma_f32_16x16x32_bf16 v[94:97], v[142:145], v[178:181], v[94:97]
	v_mfma_f32_16x16x32_bf16 v[86:89], v[150:153], v[178:181], v[86:89]
	v_mfma_f32_16x16x32_bf16 v[78:81], v[142:145], v[186:189], v[78:81]
	v_mfma_f32_16x16x32_bf16 v[70:73], v[150:153], v[186:189], v[70:73]
	v_mfma_f32_16x16x32_bf16 v[126:129], v[146:149], v[166:169], v[126:129]
	v_mfma_f32_16x16x32_bf16 v[118:121], v[158:161], v[166:169], v[118:121]
	v_mfma_f32_16x16x32_bf16 v[110:113], v[146:149], v[174:177], v[110:113]
	v_mfma_f32_16x16x32_bf16 v[102:105], v[158:161], v[174:177], v[102:105]
	v_mfma_f32_16x16x32_bf16 v[94:97], v[146:149], v[182:185], v[94:97]
	v_mfma_f32_16x16x32_bf16 v[86:89], v[158:161], v[182:185], v[86:89]
	v_mfma_f32_16x16x32_bf16 v[78:81], v[146:149], v[190:193], v[78:81]
	v_mfma_f32_16x16x32_bf16 v[70:73], v[158:161], v[190:193], v[70:73]
	s_setprio 0
	s_barrier
; #define PG8_STAGE(bufoff, gbase, voff) do { _Pragma("unroll") for (int _i = 0; _i < 2; ++_i) \
;         __builtin_amdgcn_global_load_lds((const unsigned*)((const char*)(gbase) + (voff)[_i]), (PG8_LAS unsigned*)(lds + (bufoff) + ldsw + _i * 8192), 16, 0, 0); } while (0)
; #define PG8_LDA(dst, b, h) do { int aoff; asm volatile("v_add_u32 %0, %1, %2" : "=v"(aoff) : "s"(ua), "v"(foff)); _Pragma("unroll") for (int m = 0; m < 4; ++m) _Pragma("unroll") for (int k = 0; k < 2; ++k) dst[m][k] = *(const PG8_LAS bf16x8*)(lds + PG8_SA(b, h) + aoff + m * 2048 + k * 1024); } while (0)
; #define PG8_LDB(dst, b, h) do { int boff; asm volatile("v_add_u32 %0, %1, %2" : "=v"(boff) : "s"(ub), "v"(foff)); _Pragma("unroll") for (int n = 0; n < 2; ++n) _Pragma("unroll") for (int k = 0; k < 2; ++k) dst[n][k] = *(const PG8_LAS bf16x8*)(lds + PG8_SB(b, h) + boff + n * 2048 + k * 1024); } while (0)
; #define PG8_WAIT_V(n) asm volatile("s_waitcnt vmcnt(" #n ")" ::: "memory")
; template <class Epi, class Sched>
; __device__ __forceinline__ void gemm_phase(PG8_LAS unsigned char* lds, const Gemm g, const Sched& S, const Epi& E) {
;     ...
;             PG8_LDB(B0, 0, 0); PG8_SCHED; PG8_LDA(At, 0, 0); PG8_STAGE(PG8_SA(1, 1), a1 + hstep, voffA);
;             PG8_WAIT_L(8); PG8_BAR; PG8_WAIT_L(0); PG8_MMA(0, 0, At, B0); PG8_BAR; PG8_SCHED;
;             PG8_LDB(B1, 0, 1); PG8_STAGE(PG8_SB(0, 0), b2, voffB);
;             PG8_BAR; PG8_WAIT_L(0); PG8_MMA(0, 1, At, B1); PG8_BAR;
;             PG8_LDA(At, 0, 1); PG8_STAGE(PG8_SA(0, 0), a2, voffA);
;             PG8_BAR; PG8_WAIT_L(0); PG8_MMA(1, 0, At, B0); PG8_BAR; PG8_SCHED;
;             PG8_STAGE(PG8_SB(0, 1), b2 + hstep, voffB);
;             PG8_WAIT_V(6); PG8_BAR; PG8_MMA(1, 1, At, B1); PG8_BAR;
;             PG8_LDB(B0, 1, 0); PG8_SCHED; PG8_LDA(At, 1, 0); PG8_STAGE(PG8_SA(0, 1), a2 + hstep, voffA);
;             PG8_WAIT_L(8); PG8_BAR; PG8_WAIT_L(0); PG8_MMA(0, 0, At, B0); PG8_BAR; PG8_SCHED;
;             PG8_LDB(B1, 1, 1); PG8_STAGE(PG8_SB(1, 0), b3, voffB);
;             PG8_BAR; PG8_WAIT_L(0); PG8_MMA(0, 1, At, B1); PG8_BAR;
;             PG8_LDA(At, 1, 1); PG8_STAGE(PG8_SA(1, 0), a3, voffA);
;             PG8_BAR; PG8_WAIT_L(0); PG8_MMA(1, 0, At, B0); PG8_BAR; PG8_SCHED;
;             PG8_STAGE(PG8_SB(1, 1), b3 + hstep, voffB);
;             PG8_WAIT_V(6); PG8_BAR; PG8_MMA(1, 1, At, B1); PG8_BAR;
	s_add_i32 s78, 0, 0x14000
	s_add_i32 s75, s75, s11
	v_add_u32 v194, s51, v1
	v_lshl_add_u64 v[212:213], s[44:45], 0, v[134:135]
	v_add_u32_e32 v206, s78, v194
	s_mov_b32 m0, s75
	ds_read_b128 v[194:197], v206
	ds_read_b128 v[198:201], v206 offset:1024
	ds_read_b128 v[202:205], v206 offset:2048
	ds_read_b128 v[206:209], v206 offset:3072
	global_load_lds_dwordx4 v[212:213], off
	v_lshl_add_u64 v[214:215], s[44:45], 0, v[130:131]
	s_add_i32 m0, s75, 0x2000
	s_nop 0
	global_load_lds_dwordx4 v[214:215], off
	s_barrier
	s_waitcnt lgkmcnt(0)
	s_setprio 1
	s_waitcnt lgkmcnt(0)
	v_mfma_f32_16x16x32_bf16 v[122:125], v[194:197], v[162:165], v[122:125]
	v_mfma_f32_16x16x32_bf16 v[114:117], v[202:205], v[162:165], v[114:117]
	v_mfma_f32_16x16x32_bf16 v[106:109], v[194:197], v[170:173], v[106:109]
	v_mfma_f32_16x16x32_bf16 v[98:101], v[202:205], v[170:173], v[98:101]
	v_mfma_f32_16x16x32_bf16 v[90:93], v[194:197], v[178:181], v[90:93]
	v_mfma_f32_16x16x32_bf16 v[82:85], v[202:205], v[178:181], v[82:85]
	v_mfma_f32_16x16x32_bf16 v[74:77], v[194:197], v[186:189], v[74:77]
	v_mfma_f32_16x16x32_bf16 v[66:69], v[202:205], v[186:189], v[66:69]
	v_mfma_f32_16x16x32_bf16 v[122:125], v[198:201], v[166:169], v[122:125]
	v_mfma_f32_16x16x32_bf16 v[114:117], v[206:209], v[166:169], v[114:117]
	v_mfma_f32_16x16x32_bf16 v[106:109], v[198:201], v[174:177], v[106:109]
	v_mfma_f32_16x16x32_bf16 v[98:101], v[206:209], v[174:177], v[98:101]
	v_mfma_f32_16x16x32_bf16 v[90:93], v[198:201], v[182:185], v[90:93]
	v_mfma_f32_16x16x32_bf16 v[82:85], v[206:209], v[182:185], v[82:85]
	v_mfma_f32_16x16x32_bf16 v[74:77], v[198:201], v[190:193], v[74:77]
	v_mfma_f32_16x16x32_bf16 v[66:69], v[206:209], v[190:193], v[66:69]
	s_setprio 0
	s_mov_b32 m0, s3
	s_barrier
	v_add_u32 v162, s50, v1
	v_lshl_add_u64 v[218:219], s[46:47], 0, v[136:137]
	v_add_u32_e32 v190, 0, v162
	ds_read_b128 v[162:165], v190 offset:16384
	ds_read_b128 v[166:169], v190 offset:17408
	ds_read_b128 v[170:173], v190 offset:18432
	ds_read_b128 v[174:177], v190 offset:19456
	ds_read_b128 v[178:181], v190 offset:20480
	ds_read_b128 v[182:185], v190 offset:21504
	ds_read_b128 v[186:189], v190 offset:22528
	ds_read_b128 v[190:193], v190 offset:23552
	global_load_lds_dwordx4 v[218:219], off
	v_lshl_add_u64 v[220:221], s[46:47], 0, v[132:133]
	s_mov_b32 m0, s17
	s_nop 0
	global_load_lds_dwordx4 v[220:221], off
	s_barrier
	s_waitcnt lgkmcnt(0)
	s_setprio 1
	s_waitcnt lgkmcnt(0)
	v_mfma_f32_16x16x32_bf16 v[62:65], v[142:145], v[162:165], v[62:65]
	v_mfma_f32_16x16x32_bf16 v[54:57], v[150:153], v[162:165], v[54:57]
	v_mfma_f32_16x16x32_bf16 v[46:49], v[142:145], v[170:173], v[46:49]
	v_mfma_f32_16x16x32_bf16 v[38:41], v[150:153], v[170:173], v[38:41]
	v_mfma_f32_16x16x32_bf16 v[30:33], v[142:145], v[178:181], v[30:33]
	v_mfma_f32_16x16x32_bf16 v[22:25], v[150:153], v[178:181], v[22:25]
	v_mfma_f32_16x16x32_bf16 v[14:17], v[142:145], v[186:189], v[14:17]
	v_mfma_f32_16x16x32_bf16 v[6:9], v[150:153], v[186:189], v[6:9]
	v_mfma_f32_16x16x32_bf16 v[62:65], v[146:149], v[166:169], v[62:65]
	v_mfma_f32_16x16x32_bf16 v[54:57], v[158:161], v[166:169], v[54:57]
	v_mfma_f32_16x16x32_bf16 v[46:49], v[146:149], v[174:177], v[46:49]
	v_mfma_f32_16x16x32_bf16 v[38:41], v[158:161], v[174:177], v[38:41]
	v_mfma_f32_16x16x32_bf16 v[30:33], v[146:149], v[182:185], v[30:33]
	v_mfma_f32_16x16x32_bf16 v[22:25], v[158:161], v[182:185], v[22:25]
	v_mfma_f32_16x16x32_bf16 v[14:17], v[146:149], v[190:193], v[14:17]
	v_mfma_f32_16x16x32_bf16 v[6:9], v[158:161], v[190:193], v[6:9]
	s_setprio 0
	s_barrier
	s_add_u32 s76, s44, 0x40000
	s_addc_u32 s77, s45, 0
	s_add_i32 s75, s78, s11
	v_lshl_add_u64 v[142:143], s[76:77], 0, v[134:135]
	s_mov_b32 m0, s75
	s_nop 0
	global_load_lds_dwordx4 v[142:143], off
	v_lshl_add_u64 v[142:143], s[76:77], 0, v[130:131]
	s_add_i32 m0, s75, 0x2000
	s_nop 0
	global_load_lds_dwordx4 v[142:143], off
	s_waitcnt vmcnt(6)
	s_barrier
	s_setprio 1
	v_mfma_f32_16x16x32_bf16 v[58:61], v[194:197], v[162:165], v[58:61]
	v_mfma_f32_16x16x32_bf16 v[50:53], v[202:205], v[162:165], v[50:53]
	v_mfma_f32_16x16x32_bf16 v[42:45], v[194:197], v[170:173], v[42:45]
	v_mfma_f32_16x16x32_bf16 v[34:37], v[202:205], v[170:173], v[34:37]
	v_mfma_f32_16x16x32_bf16 v[26:29], v[194:197], v[178:181], v[26:29]
	v_mfma_f32_16x16x32_bf16 v[18:21], v[202:205], v[178:181], v[18:21]
	v_mfma_f32_16x16x32_bf16 v[10:13], v[194:197], v[186:189], v[10:13]
	v_mfma_f32_16x16x32_bf16 v[2:5], v[202:205], v[186:189], v[2:5]
	v_mfma_f32_16x16x32_bf16 v[58:61], v[198:201], v[166:169], v[58:61]
	v_mfma_f32_16x16x32_bf16 v[50:53], v[206:209], v[166:169], v[50:53]
	v_mfma_f32_16x16x32_bf16 v[42:45], v[198:201], v[174:177], v[42:45]
	v_mfma_f32_16x16x32_bf16 v[34:37], v[206:209], v[174:177], v[34:37]
	v_mfma_f32_16x16x32_bf16 v[26:29], v[198:201], v[182:185], v[26:29]
	v_mfma_f32_16x16x32_bf16 v[18:21], v[206:209], v[182:185], v[18:21]
	v_mfma_f32_16x16x32_bf16 v[10:13], v[198:201], v[190:193], v[10:13]
	v_mfma_f32_16x16x32_bf16 v[2:5], v[206:209], v[190:193], v[2:5]
	s_setprio 0
	s_add_i32 s75, 0, 0x18000
	s_barrier
	v_add_u32 v142, s51, v1
	s_nop 0
	v_add_u32_e32 v158, s75, v142
	ds_read_b128 v[142:145], v158
	ds_read_b128 v[146:149], v158 offset:1024
	ds_read_b128 v[150:153], v158 offset:2048
	ds_read_b128 v[158:161], v158 offset:3072
	s_add_u32 s46, s46, 0x40000
	s_addc_u32 s47, s47, 0
	s_mov_b32 m0, s48
	v_add_u32 v162, s50, v1
	v_lshl_add_u64 v[194:195], s[46:47], 0, v[136:137]
	v_add_u32_e32 v190, 0, v162
	ds_read_b128 v[162:165], v190 offset:32768
	ds_read_b128 v[166:169], v190 offset:33792
	ds_read_b128 v[170:173], v190 offset:34816
	ds_read_b128 v[174:177], v190 offset:35840
	ds_read_b128 v[178:181], v190 offset:36864
	ds_read_b128 v[182:185], v190 offset:37888
	ds_read_b128 v[186:189], v190 offset:38912
	ds_read_b128 v[190:193], v190 offset:39936
	global_load_lds_dwordx4 v[194:195], off
	v_lshl_add_u64 v[194:195], s[46:47], 0, v[132:133]
	s_mov_b32 m0, s49
	s_nop 0
	global_load_lds_dwordx4 v[194:195], off
	s_waitcnt lgkmcnt(8)
	s_barrier
; #define PG8_STAGE(bufoff, gbase, voff) do { _Pragma("unroll") for (int _i = 0; _i < 2; ++_i) \
;         __builtin_amdgcn_global_load_lds((const unsigned*)((const char*)(gbase) + (voff)[_i]), (PG8_LAS unsigned*)(lds + (bufoff) + ldsw + _i * 8192), 16, 0, 0); } while (0)
; #define PG8_LDA(dst, b, h) do { int aoff; asm volatile("v_add_u32 %0, %1, %2" : "=v"(aoff) : "s"(ua), "v"(foff)); _Pragma("unroll") for (int m = 0; m < 4; ++m) _Pragma("unroll") for (int k = 0; k < 2; ++k) dst[m][k] = *(const PG8_LAS bf16x8*)(lds + PG8_SA(b, h) + aoff + m * 2048 + k * 1024); } while (0)
; #define PG8_LDB(dst, b, h) do { int boff; asm volatile("v_add_u32 %0, %1, %2" : "=v"(boff) : "s"(ub), "v"(foff)); _Pragma("unroll") for (int n = 0; n < 2; ++n) _Pragma("unroll") for (int k = 0; k < 2; ++k) dst[n][k] = *(const PG8_LAS bf16x8*)(lds + PG8_SB(b, h) + boff + n * 2048 + k * 1024); } while (0)
; #define PG8_MMA(ai, bj, At, Bt) do { __builtin_amdgcn_s_setprio(1); _Pragma("unroll") for (int m = 0; m < 4; ++m) _Pragma("unroll") for (int n = 0; n < 2; ++n) _Pragma("unroll") for (int k = 0; k < 2; ++k) \
;         acc[ai][bj][m][n] = __builtin_amdgcn_mfma_f32_16x16x32_bf16(Bt[n][k], At[m][k], acc[ai][bj][m][n], 0, 0, 0); __builtin_amdgcn_s_setprio(0); } while (0)
; #define PG8_WAIT_V(n) asm volatile("s_waitcnt vmcnt(" #n ")" ::: "memory")
; #define PG8_WAIT_L(n) asm volatile("s_waitcnt lgkmcnt(" #n ")" ::: "memory")
; #define PG8_BAR __builtin_amdgcn_s_barrier()
; #define PG8_SCHED __builtin_amdgcn_sched_barrier(0)
; template <class Epi, class Sched>
; __device__ __forceinline__ void gemm_phase(PG8_LAS unsigned char* lds, const Gemm g, const Sched& S, const Epi& E) {
;     ...
;             PG8_LDB(B0, 1, 0); PG8_SCHED; PG8_LDA(At, 1, 0); PG8_STAGE(PG8_SA(0, 1), a2 + hstep, voffA);
;             PG8_WAIT_L(8); PG8_BAR; PG8_WAIT_L(0); PG8_MMA(0, 0, At, B0); PG8_BAR; PG8_SCHED;
;             PG8_LDB(B1, 1, 1); PG8_STAGE(PG8_SB(1, 0), b3, voffB);
;             PG8_BAR; PG8_WAIT_L(0); PG8_MMA(0, 1, At, B1); PG8_BAR;
;             PG8_LDA(At, 1, 1); PG8_STAGE(PG8_SA(1, 0), a3, voffA);
;             PG8_BAR; PG8_WAIT_L(0); PG8_MMA(1, 0, At, B0); PG8_BAR; PG8_SCHED;
;             PG8_STAGE(PG8_SB(1, 1), b3 + hstep, voffB);
;             PG8_WAIT_V(6); PG8_BAR; PG8_MMA(1, 1, At, B1); PG8_BAR;
	s_waitcnt lgkmcnt(0)
	s_setprio 1
	s_waitcnt lgkmcnt(0)
	v_mfma_f32_16x16x32_bf16 v[126:129], v[142:145], v[162:165], v[126:129]
	v_mfma_f32_16x16x32_bf16 v[118:121], v[150:153], v[162:165], v[118:121]
	v_mfma_f32_16x16x32_bf16 v[110:113], v[142:145], v[170:173], v[110:113]
	v_mfma_f32_16x16x32_bf16 v[102:105], v[150:153], v[170:173], v[102:105]
	v_mfma_f32_16x16x32_bf16 v[94:97], v[142:145], v[178:181], v[94:97]
	v_mfma_f32_16x16x32_bf16 v[86:89], v[150:153], v[178:181], v[86:89]
	v_mfma_f32_16x16x32_bf16 v[78:81], v[142:145], v[186:189], v[78:81]
	v_mfma_f32_16x16x32_bf16 v[70:73], v[150:153], v[186:189], v[70:73]
	v_mfma_f32_16x16x32_bf16 v[126:129], v[146:149], v[166:169], v[126:129]
	v_mfma_f32_16x16x32_bf16 v[118:121], v[158:161], v[166:169], v[118:121]
	v_mfma_f32_16x16x32_bf16 v[110:113], v[146:149], v[174:177], v[110:113]
	v_mfma_f32_16x16x32_bf16 v[102:105], v[158:161], v[174:177], v[102:105]
	v_mfma_f32_16x16x32_bf16 v[94:97], v[146:149], v[182:185], v[94:97]
	v_mfma_f32_16x16x32_bf16 v[86:89], v[158:161], v[182:185], v[86:89]
	v_mfma_f32_16x16x32_bf16 v[78:81], v[146:149], v[190:193], v[78:81]
	v_mfma_f32_16x16x32_bf16 v[70:73], v[158:161], v[190:193], v[70:73]
	s_setprio 0
	s_barrier
	s_add_i32 s46, 0, 0x1c000
	s_add_i32 s47, s75, s11
	v_add_u32 v194, s51, v1
	v_lshl_add_u64 v[212:213], v[212:213], 0, s[30:31]
	v_add_u32_e32 v206, s46, v194
	s_mov_b32 m0, s47
	ds_read_b128 v[194:197], v206
	ds_read_b128 v[198:201], v206 offset:1024
	ds_read_b128 v[202:205], v206 offset:2048
	ds_read_b128 v[206:209], v206 offset:3072
	global_load_lds_dwordx4 v[212:213], off
	v_lshl_add_u64 v[212:213], v[214:215], 0, s[30:31]
	s_add_i32 m0, s47, 0x2000
	s_nop 0
	global_load_lds_dwordx4 v[212:213], off
	s_barrier
	s_waitcnt lgkmcnt(0)
	s_setprio 1
	s_waitcnt lgkmcnt(0)
	v_mfma_f32_16x16x32_bf16 v[122:125], v[194:197], v[162:165], v[122:125]
	v_mfma_f32_16x16x32_bf16 v[114:117], v[202:205], v[162:165], v[114:117]
	v_mfma_f32_16x16x32_bf16 v[106:109], v[194:197], v[170:173], v[106:109]
	v_mfma_f32_16x16x32_bf16 v[98:101], v[202:205], v[170:173], v[98:101]
	v_mfma_f32_16x16x32_bf16 v[90:93], v[194:197], v[178:181], v[90:93]
	v_mfma_f32_16x16x32_bf16 v[82:85], v[202:205], v[178:181], v[82:85]
	v_mfma_f32_16x16x32_bf16 v[74:77], v[194:197], v[186:189], v[74:77]
	v_mfma_f32_16x16x32_bf16 v[66:69], v[202:205], v[186:189], v[66:69]
	v_mfma_f32_16x16x32_bf16 v[122:125], v[198:201], v[166:169], v[122:125]
	v_mfma_f32_16x16x32_bf16 v[114:117], v[206:209], v[166:169], v[114:117]
	v_mfma_f32_16x16x32_bf16 v[106:109], v[198:201], v[174:177], v[106:109]
	v_mfma_f32_16x16x32_bf16 v[98:101], v[206:209], v[174:177], v[98:101]
	v_mfma_f32_16x16x32_bf16 v[90:93], v[198:201], v[182:185], v[90:93]
	v_mfma_f32_16x16x32_bf16 v[82:85], v[206:209], v[182:185], v[82:85]
	v_mfma_f32_16x16x32_bf16 v[74:77], v[198:201], v[190:193], v[74:77]
	v_mfma_f32_16x16x32_bf16 v[66:69], v[206:209], v[190:193], v[66:69]
	s_setprio 0
	s_mov_b32 m0, s52
	s_barrier
	v_add_u32 v162, s50, v1
	v_lshl_add_u64 v[212:213], v[218:219], 0, s[30:31]
	v_add_u32_e32 v190, 0, v162
	ds_read_b128 v[162:165], v190 offset:49152
	ds_read_b128 v[166:169], v190 offset:50176
	ds_read_b128 v[170:173], v190 offset:51200
	ds_read_b128 v[174:177], v190 offset:52224
	ds_read_b128 v[178:181], v190 offset:53248
	ds_read_b128 v[182:185], v190 offset:54272
	ds_read_b128 v[186:189], v190 offset:55296
	ds_read_b128 v[190:193], v190 offset:56320
	global_load_lds_dwordx4 v[212:213], off
	v_lshl_add_u64 v[212:213], v[220:221], 0, s[30:31]
	s_mov_b32 m0, s53
	s_nop 0
	global_load_lds_dwordx4 v[212:213], off
	s_barrier
	s_waitcnt lgkmcnt(0)
	s_setprio 1
	s_waitcnt lgkmcnt(0)
	v_mfma_f32_16x16x32_bf16 v[62:65], v[142:145], v[162:165], v[62:65]
	v_mfma_f32_16x16x32_bf16 v[54:57], v[150:153], v[162:165], v[54:57]
	v_mfma_f32_16x16x32_bf16 v[46:49], v[142:145], v[170:173], v[46:49]
	v_mfma_f32_16x16x32_bf16 v[38:41], v[150:153], v[170:173], v[38:41]
	v_mfma_f32_16x16x32_bf16 v[30:33], v[142:145], v[178:181], v[30:33]
	v_mfma_f32_16x16x32_bf16 v[22:25], v[150:153], v[178:181], v[22:25]
	v_mfma_f32_16x16x32_bf16 v[14:17], v[142:145], v[186:189], v[14:17]
	v_mfma_f32_16x16x32_bf16 v[6:9], v[150:153], v[186:189], v[6:9]
	v_mfma_f32_16x16x32_bf16 v[62:65], v[146:149], v[166:169], v[62:65]
	v_mfma_f32_16x16x32_bf16 v[54:57], v[158:161], v[166:169], v[54:57]
	v_mfma_f32_16x16x32_bf16 v[46:49], v[146:149], v[174:177], v[46:49]
	v_mfma_f32_16x16x32_bf16 v[38:41], v[158:161], v[174:177], v[38:41]
	v_mfma_f32_16x16x32_bf16 v[30:33], v[146:149], v[182:185], v[30:33]
	v_mfma_f32_16x16x32_bf16 v[22:25], v[158:161], v[182:185], v[22:25]
	v_mfma_f32_16x16x32_bf16 v[14:17], v[146:149], v[190:193], v[14:17]
	v_mfma_f32_16x16x32_bf16 v[6:9], v[158:161], v[190:193], v[6:9]
	s_setprio 0
	s_barrier
	s_add_u32 s44, s44, 0x40080
	s_addc_u32 s45, s45, 0
	s_add_i32 s46, s46, s11
	v_lshl_add_u64 v[142:143], s[44:45], 0, v[134:135]
	s_mov_b32 m0, s46
	s_nop 0
	global_load_lds_dwordx4 v[142:143], off
	v_lshl_add_u64 v[142:143], s[44:45], 0, v[130:131]
	s_add_i32 m0, s46, 0x2000
	s_nop 0
	global_load_lds_dwordx4 v[142:143], off
	s_waitcnt vmcnt(6)
	s_barrier
; __device__ __forceinline__ unsigned cvt_pk_bf16(float lo, float hi) { const f32x2c f = {lo, hi}; return __builtin_bit_cast(unsigned, __builtin_convertvector(f, bf16x2c)); }
; __device__ __forceinline__ float silu_f(float g) { return g * __builtin_amdgcn_rcpf(1.0f + __expf(-g)); }
; #define PG8_STAGE(bufoff, gbase, voff) do { _Pragma("unroll") for (int _i = 0; _i < 2; ++_i) \
;         __builtin_amdgcn_global_load_lds((const unsigned*)((const char*)(gbase) + (voff)[_i]), (PG8_LAS unsigned*)(lds + (bufoff) + ldsw + _i * 8192), 16, 0, 0); } while (0)
; #define PG8_WAIT_V(n) asm volatile("s_waitcnt vmcnt(" #n ")" ::: "memory")
;     __device__ __forceinline__ void operator()(const f32x4 (&acc)[2][2][4][2], const Unit& u, int wr, int wc, int fr, int fq) const {
;         const int row0 = u.pm * BM + wr * 64 + fr; const int col0 = u.pn * HALF + wc * 32 + 8 * fq;
; #pragma unroll
;         for (int ai = 0; ai < 2; ++ai)
; #pragma unroll
;             for (int m = 0; m < 4; ++m) { bf16_t* rowp = H + (size_t)(row0 + ai * HALF + m * 16) * ldh + col0;
;                 const f32x4 g0 = acc[ai][0][m][0], g1 = acc[ai][0][m][1], u0 = acc[ai][1][m][0], u1 = acc[ai][1][m][1];
;                 u32x4 w; w.x = cvt_pk_bf16(silu_f(g0[0]) * u0[0], silu_f(g0[1]) * u0[1]); w.y = cvt_pk_bf16(silu_f(g0[2]) * u0[2], silu_f(g0[3]) * u0[3]);
;                 w.z = cvt_pk_bf16(silu_f(g1[0]) * u1[0], silu_f(g1[1]) * u1[1]); w.w = cvt_pk_bf16(silu_f(g1[2]) * u1[2], silu_f(g1[3]) * u1[3]);
;                 *(u32x4*)rowp = w; }
; template <class Epi, class Sched>
; __device__ __forceinline__ void gemm_phase(PG8_LAS unsigned char* lds, const Gemm g, const Sched& S, const Epi& E) {
;     ...
;             PG8_WAIT_V(6); PG8_BAR; PG8_MMA(1, 1, At, B1); PG8_BAR;
;             PG8_LDB(B0, 1, 0); PG8_SCHED; PG8_LDA(At, 1, 0); PG8_STAGE(PG8_SA(0, 1), a2 + hstep, voffA);
;             PG8_WAIT_L(8); PG8_BAR; PG8_WAIT_L(0); PG8_MMA(0, 0, At, B0); PG8_BAR; PG8_SCHED;
;             PG8_LDB(B1, 1, 1); PG8_STAGE(PG8_SB(1, 0), b3, voffB);
;             PG8_BAR; PG8_WAIT_L(0); PG8_MMA(0, 1, At, B1); PG8_BAR;
;             PG8_LDA(At, 1, 1); PG8_STAGE(PG8_SA(1, 0), a3, voffA);
;             PG8_BAR; PG8_WAIT_L(0); PG8_MMA(1, 0, At, B0); PG8_BAR; PG8_SCHED;
;             PG8_STAGE(PG8_SB(1, 1), b3 + hstep, voffB);
;             PG8_WAIT_V(6); PG8_BAR; PG8_MMA(1, 1, At, B1); PG8_BAR;
;         }
	s_setprio 1
	v_mfma_f32_16x16x32_bf16 v[58:61], v[194:197], v[162:165], v[58:61]
	v_mfma_f32_16x16x32_bf16 v[50:53], v[202:205], v[162:165], v[50:53]
	v_mfma_f32_16x16x32_bf16 v[42:45], v[194:197], v[170:173], v[42:45]
	v_mfma_f32_16x16x32_bf16 v[34:37], v[202:205], v[170:173], v[34:37]
	v_mfma_f32_16x16x32_bf16 v[26:29], v[194:197], v[178:181], v[26:29]
	v_mfma_f32_16x16x32_bf16 v[18:21], v[202:205], v[178:181], v[18:21]
	v_mfma_f32_16x16x32_bf16 v[10:13], v[194:197], v[186:189], v[10:13]
	v_mfma_f32_16x16x32_bf16 v[2:5], v[202:205], v[186:189], v[2:5]
	v_mfma_f32_16x16x32_bf16 v[58:61], v[198:201], v[166:169], v[58:61]
	v_mfma_f32_16x16x32_bf16 v[50:53], v[206:209], v[166:169], v[50:53]
	v_mfma_f32_16x16x32_bf16 v[42:45], v[198:201], v[174:177], v[42:45]
	v_mfma_f32_16x16x32_bf16 v[34:37], v[206:209], v[174:177], v[34:37]
	v_mfma_f32_16x16x32_bf16 v[26:29], v[198:201], v[182:185], v[26:29]
	v_mfma_f32_16x16x32_bf16 v[18:21], v[206:209], v[182:185], v[18:21]
	v_mfma_f32_16x16x32_bf16 v[10:13], v[198:201], v[190:193], v[10:13]
	v_mfma_f32_16x16x32_bf16 v[2:5], v[206:209], v[190:193], v[2:5]
	s_setprio 0
	s_add_i32 s74, s74, 2
	s_add_u32 s26, s26, 0x100
	s_addc_u32 s27, s27, 0
	s_add_u32 s62, s62, 0x100
	s_addc_u32 s63, s63, 0
	s_cmp_gt_u32 s74, 13
	s_barrier
	s_cbranch_scc0 .LBB0_1109
	v_mul_f32_e32 v148, 0xbfb8aa3b, v126
	v_mul_f32_e32 v149, 0xbfb8aa3b, v127
	v_exp_f32_e32 v148, v148
	v_exp_f32_e32 v149, v149
	v_add_f32_e32 v148, 1.0, v148
	v_add_f32_e32 v149, 1.0, v149
	v_rcp_f32_e32 v148, v148
	v_rcp_f32_e32 v149, v149
	v_lshl_or_b32 v144, s2, 7, v157
	v_pk_mul_f32 v[126:127], v[126:127], v[148:149]
	s_movk_i32 s2, 0x1600
	v_pk_mul_f32 v[122:123], v[126:127], v[122:123]
	v_lshl_add_u32 v158, s16, 8, v156
	v_cvt_pk_bf16_f32 v122, v122, v123
	v_mul_f32_e32 v123, 0xbfb8aa3b, v128
	v_exp_f32_e32 v123, v123
	v_ashrrev_i32_e32 v145, 31, v144
	v_add_f32_e32 v123, 1.0, v123
	v_rcp_f32_e32 v126, v123
	v_mul_f32_e32 v123, 0xbfb8aa3b, v129
	v_exp_f32_e32 v123, v123
	v_mov_b64_e32 v[142:143], s[68:69]
	v_add_f32_e32 v123, 1.0, v123
	v_rcp_f32_e32 v127, v123
	s_and_b64 vcc, exec, s[38:39]
	v_pk_mul_f32 v[126:127], v[128:129], v[126:127]
	v_mad_i64_i32 v[146:147], s[26:27], v158, s2, v[142:143]
	v_pk_mul_f32 v[124:125], v[126:127], v[124:125]
	v_lshlrev_b64 v[144:145], 1, v[144:145]
	v_cvt_pk_bf16_f32 v123, v124, v125
	v_mul_f32_e32 v124, 0xbfb8aa3b, v118
	v_mul_f32_e32 v125, 0xbfb8aa3b, v119
	v_exp_f32_e32 v124, v124
	v_exp_f32_e32 v125, v125
	v_add_f32_e32 v124, 1.0, v124
	v_add_f32_e32 v125, 1.0, v125
	v_rcp_f32_e32 v124, v124
	v_rcp_f32_e32 v125, v125
	s_mov_b32 s16, s20
	v_pk_mul_f32 v[118:119], v[118:119], v[124:125]
	v_lshl_add_u64 v[146:147], v[146:147], 0, v[144:145]
	v_pk_mul_f32 v[114:115], v[118:119], v[114:115]
	s_mov_b64 s[44:45], s[28:29]
	v_cvt_pk_bf16_f32 v124, v114, v115
	v_mul_f32_e32 v114, 0xbfb8aa3b, v120
	v_mul_f32_e32 v115, 0xbfb8aa3b, v121
	v_exp_f32_e32 v114, v114
	v_exp_f32_e32 v115, v115
	v_add_f32_e32 v114, 1.0, v114
	v_add_f32_e32 v115, 1.0, v115
	v_rcp_f32_e32 v114, v114
	v_rcp_f32_e32 v115, v115
	v_mov_b32_e32 v118, 0
	v_pk_mul_f32 v[114:115], v[120:121], v[114:115]
	v_mov_b32_e32 v119, 0
	v_pk_mul_f32 v[114:115], v[114:115], v[116:117]
	v_mul_f32_e32 v116, 0xbfb8aa3b, v110
	v_mul_f32_e32 v117, 0xbfb8aa3b, v111
	v_exp_f32_e32 v116, v116
	v_exp_f32_e32 v117, v117
	v_add_f32_e32 v116, 1.0, v116
	v_add_f32_e32 v117, 1.0, v117
	v_rcp_f32_e32 v116, v116
	v_rcp_f32_e32 v117, v117
	v_cvt_pk_bf16_f32 v125, v114, v115
	v_pk_mul_f32 v[110:111], v[110:111], v[116:117]
	v_or_b32_e32 v114, 16, v158
	v_pk_mul_f32 v[106:107], v[110:111], v[106:107]
	v_mad_i64_i32 v[114:115], s[26:27], v114, s2, v[142:143]
	v_cvt_pk_bf16_f32 v106, v106, v107
	v_mul_f32_e32 v107, 0xbfb8aa3b, v112
	v_exp_f32_e32 v107, v107
	v_lshl_add_u64 v[114:115], v[114:115], 0, v[144:145]
	v_add_f32_e32 v107, 1.0, v107
	v_rcp_f32_e32 v110, v107
	v_mul_f32_e32 v107, 0xbfb8aa3b, v113
	v_exp_f32_e32 v107, v107
	global_store_dwordx4 v[146:147], v[122:125], off
	v_add_f32_e32 v107, 1.0, v107
	v_rcp_f32_e32 v111, v107
	v_mov_b32_e32 v116, 0
	v_pk_mul_f32 v[110:111], v[112:113], v[110:111]
	v_mov_b32_e32 v112, 0
	v_pk_mul_f32 v[108:109], v[110:111], v[108:109]
	v_mov_b32_e32 v110, 0
	v_cvt_pk_bf16_f32 v107, v108, v109
	v_mul_f32_e32 v108, 0xbfb8aa3b, v102
	v_mul_f32_e32 v109, 0xbfb8aa3b, v103
	v_exp_f32_e32 v108, v108
	v_exp_f32_e32 v109, v109
	v_add_f32_e32 v108, 1.0, v108
	v_add_f32_e32 v109, 1.0, v109
	v_rcp_f32_e32 v108, v108
	v_rcp_f32_e32 v109, v109
	v_mov_b32_e32 v111, 0
	v_pk_mul_f32 v[102:103], v[102:103], v[108:109]
	v_mov_b32_e32 v113, 0
	v_pk_mul_f32 v[98:99], v[102:103], v[98:99]
	v_mov_b32_e32 v102, 0
	v_cvt_pk_bf16_f32 v108, v98, v99
	v_mul_f32_e32 v98, 0xbfb8aa3b, v104
	v_mul_f32_e32 v99, 0xbfb8aa3b, v105
	v_exp_f32_e32 v98, v98
	v_exp_f32_e32 v99, v99
	v_add_f32_e32 v98, 1.0, v98
	v_add_f32_e32 v99, 1.0, v99
	v_rcp_f32_e32 v98, v98
	v_rcp_f32_e32 v99, v99
	v_mov_b32_e32 v103, 0
	v_pk_mul_f32 v[98:99], v[104:105], v[98:99]
	v_mov_b32_e32 v104, 0
	v_pk_mul_f32 v[98:99], v[98:99], v[100:101]
	v_mul_f32_e32 v100, 0xbfb8aa3b, v94
	v_mul_f32_e32 v101, 0xbfb8aa3b, v95
	v_exp_f32_e32 v100, v100
	v_exp_f32_e32 v101, v101
	v_add_f32_e32 v100, 1.0, v100
	v_add_f32_e32 v101, 1.0, v101
	v_rcp_f32_e32 v100, v100
	v_rcp_f32_e32 v101, v101
	v_cvt_pk_bf16_f32 v109, v98, v99
	v_pk_mul_f32 v[94:95], v[94:95], v[100:101]
	v_or_b32_e32 v98, 32, v158
	v_pk_mul_f32 v[90:91], v[94:95], v[90:91]
	v_mad_i64_i32 v[98:99], s[26:27], v98, s2, v[142:143]
	v_cvt_pk_bf16_f32 v90, v90, v91
	v_mul_f32_e32 v91, 0xbfb8aa3b, v96
	v_exp_f32_e32 v91, v91
	v_lshl_add_u64 v[98:99], v[98:99], 0, v[144:145]
; __device__ __forceinline__ unsigned cvt_pk_bf16(float lo, float hi) { const f32x2c f = {lo, hi}; return __builtin_bit_cast(unsigned, __builtin_convertvector(f, bf16x2c)); }
; __device__ __forceinline__ float silu_f(float g) { return g * __builtin_amdgcn_rcpf(1.0f + __expf(-g)); }
;     __device__ __forceinline__ void operator()(const f32x4 (&acc)[2][2][4][2], const Unit& u, int wr, int wc, int fr, int fq) const {
;         const int row0 = u.pm * BM + wr * 64 + fr; const int col0 = u.pn * HALF + wc * 32 + 8 * fq;
; #pragma unroll
;         for (int ai = 0; ai < 2; ++ai)
; #pragma unroll
;             for (int m = 0; m < 4; ++m) { bf16_t* rowp = H + (size_t)(row0 + ai * HALF + m * 16) * ldh + col0;
;                 const f32x4 g0 = acc[ai][0][m][0], g1 = acc[ai][0][m][1], u0 = acc[ai][1][m][0], u1 = acc[ai][1][m][1];
;                 u32x4 w; w.x = cvt_pk_bf16(silu_f(g0[0]) * u0[0], silu_f(g0[1]) * u0[1]); w.y = cvt_pk_bf16(silu_f(g0[2]) * u0[2], silu_f(g0[3]) * u0[3]);
;                 w.z = cvt_pk_bf16(silu_f(g1[0]) * u1[0], silu_f(g1[1]) * u1[1]); w.w = cvt_pk_bf16(silu_f(g1[2]) * u1[2], silu_f(g1[3]) * u1[3]);
;                 *(u32x4*)rowp = w; }
; template <class Epi, class Sched>
; __device__ __forceinline__ void gemm_phase(PG8_LAS unsigned char* lds, const Gemm g, const Sched& S, const Epi& E) {
;     ...
; #pragma unroll
;         for (int a = 0; a < 2; ++a)
; #pragma unroll
;             for (int b = 0; b < 2; ++b)
; #pragma unroll
;                 for (int m = 0; m < 4; ++m)
; #pragma unroll
;                     for (int n = 0; n < 2; ++n) acc[a][b][m][n] = (f32x4){0.f, 0.f, 0.f, 0.f};
	v_add_f32_e32 v91, 1.0, v91
	v_rcp_f32_e32 v94, v91
	v_mul_f32_e32 v91, 0xbfb8aa3b, v97
	v_exp_f32_e32 v91, v91
	global_store_dwordx4 v[114:115], v[106:109], off
	v_add_f32_e32 v91, 1.0, v91
	v_rcp_f32_e32 v95, v91
	v_mov_b32_e32 v100, 0
	v_pk_mul_f32 v[94:95], v[96:97], v[94:95]
	v_mov_b32_e32 v96, 0
	v_pk_mul_f32 v[92:93], v[94:95], v[92:93]
	v_mov_b32_e32 v94, 0
	v_cvt_pk_bf16_f32 v91, v92, v93
	v_mul_f32_e32 v92, 0xbfb8aa3b, v86
	v_mul_f32_e32 v93, 0xbfb8aa3b, v87
	v_exp_f32_e32 v92, v92
	v_exp_f32_e32 v93, v93
	v_add_f32_e32 v92, 1.0, v92
	v_add_f32_e32 v93, 1.0, v93
	v_rcp_f32_e32 v92, v92
	v_rcp_f32_e32 v93, v93
	v_mov_b32_e32 v95, 0
	v_pk_mul_f32 v[86:87], v[86:87], v[92:93]
	v_mov_b32_e32 v97, 0
	v_pk_mul_f32 v[82:83], v[86:87], v[82:83]
	v_mov_b32_e32 v86, 0
	v_cvt_pk_bf16_f32 v92, v82, v83
	v_mul_f32_e32 v82, 0xbfb8aa3b, v88
	v_mul_f32_e32 v83, 0xbfb8aa3b, v89
	v_exp_f32_e32 v82, v82
	v_exp_f32_e32 v83, v83
	v_add_f32_e32 v82, 1.0, v82
	v_add_f32_e32 v83, 1.0, v83
	v_rcp_f32_e32 v82, v82
	v_rcp_f32_e32 v83, v83
	v_mov_b32_e32 v87, 0
	v_pk_mul_f32 v[82:83], v[88:89], v[82:83]
	v_mov_b32_e32 v88, 0
	v_pk_mul_f32 v[82:83], v[82:83], v[84:85]
	v_mul_f32_e32 v84, 0xbfb8aa3b, v78
	v_mul_f32_e32 v85, 0xbfb8aa3b, v79
	v_exp_f32_e32 v84, v84
	v_exp_f32_e32 v85, v85
	v_add_f32_e32 v84, 1.0, v84
	v_add_f32_e32 v85, 1.0, v85
	v_rcp_f32_e32 v84, v84
	v_rcp_f32_e32 v85, v85
	v_cvt_pk_bf16_f32 v93, v82, v83
	v_pk_mul_f32 v[78:79], v[78:79], v[84:85]
	v_or_b32_e32 v82, 48, v158
	v_pk_mul_f32 v[74:75], v[78:79], v[74:75]
	v_mad_i64_i32 v[82:83], s[26:27], v82, s2, v[142:143]
	v_cvt_pk_bf16_f32 v74, v74, v75
	v_mul_f32_e32 v75, 0xbfb8aa3b, v80
	v_exp_f32_e32 v75, v75
	v_lshl_add_u64 v[82:83], v[82:83], 0, v[144:145]
	v_add_f32_e32 v75, 1.0, v75
	v_rcp_f32_e32 v78, v75
	v_mul_f32_e32 v75, 0xbfb8aa3b, v81
	v_exp_f32_e32 v75, v75
	global_store_dwordx4 v[98:99], v[90:93], off
	v_add_f32_e32 v75, 1.0, v75
	v_rcp_f32_e32 v79, v75
	v_mov_b32_e32 v84, 0
	v_pk_mul_f32 v[78:79], v[80:81], v[78:79]
	v_mov_b32_e32 v80, 0
	v_pk_mul_f32 v[76:77], v[78:79], v[76:77]
	v_mov_b32_e32 v78, 0
	v_cvt_pk_bf16_f32 v75, v76, v77
	v_mul_f32_e32 v76, 0xbfb8aa3b, v70
	v_mul_f32_e32 v77, 0xbfb8aa3b, v71
	v_exp_f32_e32 v76, v76
	v_exp_f32_e32 v77, v77
	v_add_f32_e32 v76, 1.0, v76
	v_add_f32_e32 v77, 1.0, v77
	v_rcp_f32_e32 v76, v76
	v_rcp_f32_e32 v77, v77
	v_mov_b32_e32 v79, 0
	v_pk_mul_f32 v[70:71], v[70:71], v[76:77]
	v_mov_b32_e32 v81, 0
	v_pk_mul_f32 v[66:67], v[70:71], v[66:67]
	v_mov_b32_e32 v70, 0
	v_cvt_pk_bf16_f32 v76, v66, v67
	v_mul_f32_e32 v66, 0xbfb8aa3b, v72
	v_mul_f32_e32 v67, 0xbfb8aa3b, v73
	v_exp_f32_e32 v66, v66
	v_exp_f32_e32 v67, v67
	v_add_f32_e32 v66, 1.0, v66
	v_add_f32_e32 v67, 1.0, v67
	v_rcp_f32_e32 v66, v66
	v_rcp_f32_e32 v67, v67
	v_mov_b32_e32 v71, 0
	v_pk_mul_f32 v[66:67], v[72:73], v[66:67]
	v_mov_b32_e32 v72, 0
	v_pk_mul_f32 v[66:67], v[66:67], v[68:69]
	v_mul_f32_e32 v68, 0xbfb8aa3b, v62
	v_mul_f32_e32 v69, 0xbfb8aa3b, v63
	v_exp_f32_e32 v68, v68
	v_exp_f32_e32 v69, v69
	v_add_f32_e32 v68, 1.0, v68
	v_add_f32_e32 v69, 1.0, v69
	v_rcp_f32_e32 v68, v68
	v_rcp_f32_e32 v69, v69
	v_cvt_pk_bf16_f32 v77, v66, v67
	v_pk_mul_f32 v[62:63], v[62:63], v[68:69]
	v_add_u32_e32 v66, 0x80, v158
	v_pk_mul_f32 v[58:59], v[62:63], v[58:59]
	v_mad_i64_i32 v[66:67], s[26:27], v66, s2, v[142:143]
	v_cvt_pk_bf16_f32 v58, v58, v59
	v_mul_f32_e32 v59, 0xbfb8aa3b, v64
	v_exp_f32_e32 v59, v59
	v_lshl_add_u64 v[66:67], v[66:67], 0, v[144:145]
	v_add_f32_e32 v59, 1.0, v59
	v_rcp_f32_e32 v62, v59
	v_mul_f32_e32 v59, 0xbfb8aa3b, v65
	v_exp_f32_e32 v59, v59
	global_store_dwordx4 v[82:83], v[74:77], off
	v_add_f32_e32 v59, 1.0, v59
	v_rcp_f32_e32 v63, v59
	v_mov_b32_e32 v68, 0
	v_pk_mul_f32 v[62:63], v[64:65], v[62:63]
	v_mov_b32_e32 v64, 0
	v_pk_mul_f32 v[60:61], v[62:63], v[60:61]
	v_mov_b32_e32 v62, 0
	v_cvt_pk_bf16_f32 v59, v60, v61
	v_mul_f32_e32 v60, 0xbfb8aa3b, v54
	v_mul_f32_e32 v61, 0xbfb8aa3b, v55
	v_exp_f32_e32 v60, v60
	v_exp_f32_e32 v61, v61
	v_add_f32_e32 v60, 1.0, v60
	v_add_f32_e32 v61, 1.0, v61
	v_rcp_f32_e32 v60, v60
	v_rcp_f32_e32 v61, v61
	v_mov_b32_e32 v63, 0
	v_pk_mul_f32 v[54:55], v[54:55], v[60:61]
	v_mov_b32_e32 v65, 0
	v_pk_mul_f32 v[50:51], v[54:55], v[50:51]
	v_mov_b32_e32 v54, 0
	v_cvt_pk_bf16_f32 v60, v50, v51
	v_mul_f32_e32 v50, 0xbfb8aa3b, v56
	v_mul_f32_e32 v51, 0xbfb8aa3b, v57
	v_exp_f32_e32 v50, v50
	v_exp_f32_e32 v51, v51
	v_add_f32_e32 v50, 1.0, v50
	v_add_f32_e32 v51, 1.0, v51
	v_rcp_f32_e32 v50, v50
	v_rcp_f32_e32 v51, v51
	v_mov_b32_e32 v55, 0
	v_pk_mul_f32 v[50:51], v[56:57], v[50:51]
	v_mov_b32_e32 v56, 0
	v_pk_mul_f32 v[50:51], v[50:51], v[52:53]
	v_mul_f32_e32 v52, 0xbfb8aa3b, v46
	v_mul_f32_e32 v53, 0xbfb8aa3b, v47
	v_exp_f32_e32 v52, v52
	v_exp_f32_e32 v53, v53
	v_add_f32_e32 v52, 1.0, v52
	v_add_f32_e32 v53, 1.0, v53
	v_rcp_f32_e32 v52, v52
	v_rcp_f32_e32 v53, v53
	v_cvt_pk_bf16_f32 v61, v50, v51
	v_pk_mul_f32 v[46:47], v[46:47], v[52:53]
	v_add_u32_e32 v50, 0x90, v158
	v_pk_mul_f32 v[42:43], v[46:47], v[42:43]
	v_mad_i64_i32 v[50:51], s[26:27], v50, s2, v[142:143]
	v_cvt_pk_bf16_f32 v42, v42, v43
	v_mul_f32_e32 v43, 0xbfb8aa3b, v48
	v_exp_f32_e32 v43, v43
	v_lshl_add_u64 v[50:51], v[50:51], 0, v[144:145]
	v_add_f32_e32 v43, 1.0, v43
	v_rcp_f32_e32 v46, v43
	v_mul_f32_e32 v43, 0xbfb8aa3b, v49
	v_exp_f32_e32 v43, v43
	global_store_dwordx4 v[66:67], v[58:61], off
	v_add_f32_e32 v43, 1.0, v43
	v_rcp_f32_e32 v47, v43
	v_mov_b32_e32 v52, 0
	v_pk_mul_f32 v[46:47], v[48:49], v[46:47]
	v_mov_b32_e32 v48, 0
	v_pk_mul_f32 v[44:45], v[46:47], v[44:45]
	v_mov_b32_e32 v46, 0
	v_cvt_pk_bf16_f32 v43, v44, v45
	v_mul_f32_e32 v44, 0xbfb8aa3b, v38
; __device__ __forceinline__ unsigned cvt_pk_bf16(float lo, float hi) { const f32x2c f = {lo, hi}; return __builtin_bit_cast(unsigned, __builtin_convertvector(f, bf16x2c)); }
; __device__ __forceinline__ float silu_f(float g) { return g * __builtin_amdgcn_rcpf(1.0f + __expf(-g)); }
;     __device__ __forceinline__ void operator()(const f32x4 (&acc)[2][2][4][2], const Unit& u, int wr, int wc, int fr, int fq) const {
;         const int row0 = u.pm * BM + wr * 64 + fr; const int col0 = u.pn * HALF + wc * 32 + 8 * fq;
; #pragma unroll
;         for (int ai = 0; ai < 2; ++ai)
; #pragma unroll
;             for (int m = 0; m < 4; ++m) { bf16_t* rowp = H + (size_t)(row0 + ai * HALF + m * 16) * ldh + col0;
;                 const f32x4 g0 = acc[ai][0][m][0], g1 = acc[ai][0][m][1], u0 = acc[ai][1][m][0], u1 = acc[ai][1][m][1];
;                 u32x4 w; w.x = cvt_pk_bf16(silu_f(g0[0]) * u0[0], silu_f(g0[1]) * u0[1]); w.y = cvt_pk_bf16(silu_f(g0[2]) * u0[2], silu_f(g0[3]) * u0[3]);
;                 w.z = cvt_pk_bf16(silu_f(g1[0]) * u1[0], silu_f(g1[1]) * u1[1]); w.w = cvt_pk_bf16(silu_f(g1[2]) * u1[2], silu_f(g1[3]) * u1[3]);
;                 *(u32x4*)rowp = w; }
; template <class Epi, class Sched>
; __device__ __forceinline__ void gemm_phase(PG8_LAS unsigned char* lds, const Gemm g, const Sched& S, const Epi& E) {
;     ...
; #pragma unroll
;         for (int a = 0; a < 2; ++a)
; #pragma unroll
;             for (int b = 0; b < 2; ++b)
; #pragma unroll
;                 for (int m = 0; m < 4; ++m)
; #pragma unroll
;                     for (int n = 0; n < 2; ++n) acc[a][b][m][n] = (f32x4){0.f, 0.f, 0.f, 0.f};
	v_mul_f32_e32 v45, 0xbfb8aa3b, v39
	v_exp_f32_e32 v44, v44
	v_exp_f32_e32 v45, v45
	v_add_f32_e32 v44, 1.0, v44
	v_add_f32_e32 v45, 1.0, v45
	v_rcp_f32_e32 v44, v44
	v_rcp_f32_e32 v45, v45
	v_mov_b32_e32 v47, 0
	v_pk_mul_f32 v[38:39], v[38:39], v[44:45]
	v_mov_b32_e32 v49, 0
	v_pk_mul_f32 v[34:35], v[38:39], v[34:35]
	v_mov_b32_e32 v38, 0
	v_cvt_pk_bf16_f32 v44, v34, v35
	v_mul_f32_e32 v34, 0xbfb8aa3b, v40
	v_mul_f32_e32 v35, 0xbfb8aa3b, v41
	v_exp_f32_e32 v34, v34
	v_exp_f32_e32 v35, v35
	v_add_f32_e32 v34, 1.0, v34
	v_add_f32_e32 v35, 1.0, v35
	v_rcp_f32_e32 v34, v34
	v_rcp_f32_e32 v35, v35
	v_mov_b32_e32 v39, 0
	v_pk_mul_f32 v[34:35], v[40:41], v[34:35]
	v_mov_b32_e32 v40, 0
	v_pk_mul_f32 v[34:35], v[34:35], v[36:37]
	v_mul_f32_e32 v36, 0xbfb8aa3b, v30
	v_mul_f32_e32 v37, 0xbfb8aa3b, v31
	v_exp_f32_e32 v36, v36
	v_exp_f32_e32 v37, v37
	v_add_f32_e32 v36, 1.0, v36
	v_add_f32_e32 v37, 1.0, v37
	v_rcp_f32_e32 v36, v36
	v_rcp_f32_e32 v37, v37
	v_cvt_pk_bf16_f32 v45, v34, v35
	v_pk_mul_f32 v[30:31], v[30:31], v[36:37]
	v_add_u32_e32 v34, 0xa0, v158
	v_pk_mul_f32 v[26:27], v[30:31], v[26:27]
	v_mad_i64_i32 v[34:35], s[26:27], v34, s2, v[142:143]
	v_cvt_pk_bf16_f32 v26, v26, v27
	v_mul_f32_e32 v27, 0xbfb8aa3b, v32
	v_exp_f32_e32 v27, v27
	global_store_dwordx4 v[50:51], v[42:45], off
	v_add_f32_e32 v27, 1.0, v27
	v_rcp_f32_e32 v30, v27
	v_mul_f32_e32 v27, 0xbfb8aa3b, v33
	v_exp_f32_e32 v27, v27
	v_lshl_add_u64 v[34:35], v[34:35], 0, v[144:145]
	v_add_f32_e32 v27, 1.0, v27
	v_rcp_f32_e32 v31, v27
	v_mov_b32_e32 v36, 0
	v_pk_mul_f32 v[30:31], v[32:33], v[30:31]
	v_mov_b32_e32 v32, 0
	v_pk_mul_f32 v[28:29], v[30:31], v[28:29]
	v_mov_b32_e32 v30, 0
	v_cvt_pk_bf16_f32 v27, v28, v29
	v_mul_f32_e32 v28, 0xbfb8aa3b, v22
	v_mul_f32_e32 v29, 0xbfb8aa3b, v23
	v_exp_f32_e32 v28, v28
	v_exp_f32_e32 v29, v29
	v_add_f32_e32 v28, 1.0, v28
	v_add_f32_e32 v29, 1.0, v29
	v_rcp_f32_e32 v28, v28
	v_rcp_f32_e32 v29, v29
	v_mov_b32_e32 v31, 0
	v_pk_mul_f32 v[22:23], v[22:23], v[28:29]
	v_mov_b32_e32 v33, 0
	v_pk_mul_f32 v[18:19], v[22:23], v[18:19]
	v_mov_b32_e32 v22, 0
	v_cvt_pk_bf16_f32 v28, v18, v19
	v_mul_f32_e32 v18, 0xbfb8aa3b, v24
	v_mul_f32_e32 v19, 0xbfb8aa3b, v25
	v_exp_f32_e32 v18, v18
	v_exp_f32_e32 v19, v19
	v_add_f32_e32 v18, 1.0, v18
	v_add_f32_e32 v19, 1.0, v19
	v_rcp_f32_e32 v18, v18
	v_rcp_f32_e32 v19, v19
	v_mov_b32_e32 v23, 0
	v_pk_mul_f32 v[18:19], v[24:25], v[18:19]
	v_mov_b32_e32 v24, 0
	v_pk_mul_f32 v[18:19], v[18:19], v[20:21]
	v_mul_f32_e32 v20, 0xbfb8aa3b, v14
	v_mul_f32_e32 v21, 0xbfb8aa3b, v15
	v_exp_f32_e32 v20, v20
	v_exp_f32_e32 v21, v21
	v_add_f32_e32 v20, 1.0, v20
	v_add_f32_e32 v21, 1.0, v21
	v_rcp_f32_e32 v20, v20
	v_rcp_f32_e32 v21, v21
	v_cvt_pk_bf16_f32 v29, v18, v19
	v_pk_mul_f32 v[14:15], v[14:15], v[20:21]
	v_add_u32_e32 v18, 0xb0, v158
	v_pk_mul_f32 v[10:11], v[14:15], v[10:11]
	v_mad_i64_i32 v[18:19], s[26:27], v18, s2, v[142:143]
	v_cvt_pk_bf16_f32 v10, v10, v11
	v_mul_f32_e32 v11, 0xbfb8aa3b, v16
	v_exp_f32_e32 v11, v11
	s_mov_b32 s2, s18
	v_add_f32_e32 v11, 1.0, v11
	v_rcp_f32_e32 v14, v11
	v_mul_f32_e32 v11, 0xbfb8aa3b, v17
	v_exp_f32_e32 v11, v11
	s_mov_b64 s[26:27], s[24:25]
	v_add_f32_e32 v11, 1.0, v11
	v_rcp_f32_e32 v15, v11
	v_lshl_add_u64 v[18:19], v[18:19], 0, v[144:145]
	v_pk_mul_f32 v[14:15], v[16:17], v[14:15]
	global_store_dwordx4 v[34:35], v[26:29], off
	v_pk_mul_f32 v[12:13], v[14:15], v[12:13]
	v_mov_b32_e32 v14, 0
	v_cvt_pk_bf16_f32 v11, v12, v13
	v_mul_f32_e32 v12, 0xbfb8aa3b, v6
	v_mul_f32_e32 v13, 0xbfb8aa3b, v7
	v_exp_f32_e32 v12, v12
	v_exp_f32_e32 v13, v13
	v_add_f32_e32 v12, 1.0, v12
	v_add_f32_e32 v13, 1.0, v13
	v_rcp_f32_e32 v12, v12
	v_rcp_f32_e32 v13, v13
	v_mov_b32_e32 v15, 0
	v_pk_mul_f32 v[6:7], v[6:7], v[12:13]
	v_mov_b32_e32 v16, 0
	v_pk_mul_f32 v[2:3], v[6:7], v[2:3]
	v_mov_b32_e32 v6, 0
	v_cvt_pk_bf16_f32 v12, v2, v3
	v_mul_f32_e32 v2, 0xbfb8aa3b, v8
	v_mul_f32_e32 v3, 0xbfb8aa3b, v9
	v_exp_f32_e32 v2, v2
	v_exp_f32_e32 v3, v3
	v_add_f32_e32 v2, 1.0, v2
	v_add_f32_e32 v3, 1.0, v3
	v_rcp_f32_e32 v2, v2
	v_rcp_f32_e32 v3, v3
	v_mov_b32_e32 v7, 0
	v_pk_mul_f32 v[2:3], v[8:9], v[2:3]
	v_mov_b32_e32 v8, 0
	v_pk_mul_f32 v[2:3], v[2:3], v[4:5]
	v_mov_b32_e32 v4, 0
	v_cvt_pk_bf16_f32 v13, v2, v3
	global_store_dwordx4 v[18:19], v[10:13], off
	v_mov_b32_e32 v5, 0
	v_mov_b32_e32 v9, 0
	v_mov_b32_e32 v10, 0
	v_mov_b32_e32 v11, 0
	v_mov_b32_e32 v12, 0
	v_mov_b32_e32 v13, 0
	v_mov_b32_e32 v17, 0
	v_mov_b32_e32 v18, 0
	v_mov_b32_e32 v19, 0
	v_mov_b32_e32 v20, 0
	v_mov_b32_e32 v21, 0
	v_mov_b32_e32 v25, 0
	v_mov_b32_e32 v26, 0
	v_mov_b32_e32 v27, 0
	v_mov_b32_e32 v28, 0
	v_mov_b32_e32 v29, 0
	v_mov_b32_e32 v34, 0
	v_mov_b32_e32 v35, 0
	v_mov_b32_e32 v37, 0
	v_mov_b32_e32 v41, 0
	v_mov_b32_e32 v42, 0
	v_mov_b32_e32 v43, 0
	v_mov_b32_e32 v44, 0
	v_mov_b32_e32 v45, 0
	v_mov_b32_e32 v50, 0
	v_mov_b32_e32 v51, 0
	v_mov_b32_e32 v53, 0
	v_mov_b32_e32 v57, 0
	v_mov_b32_e32 v58, 0
	v_mov_b32_e32 v59, 0
	v_mov_b32_e32 v60, 0
	v_mov_b32_e32 v61, 0
	v_mov_b32_e32 v66, 0
	v_mov_b32_e32 v67, 0
	v_mov_b32_e32 v69, 0
	v_mov_b32_e32 v73, 0
	v_mov_b32_e32 v74, 0
	v_mov_b32_e32 v75, 0
	v_mov_b32_e32 v76, 0
	v_mov_b32_e32 v77, 0
	v_mov_b32_e32 v82, 0
	v_mov_b32_e32 v83, 0
	v_mov_b32_e32 v85, 0
	v_mov_b32_e32 v89, 0
	v_mov_b32_e32 v90, 0
	v_mov_b32_e32 v91, 0
	v_mov_b32_e32 v92, 0
	v_mov_b32_e32 v93, 0
	v_mov_b32_e32 v98, 0
	v_mov_b32_e32 v99, 0
	v_mov_b32_e32 v101, 0
	v_mov_b32_e32 v105, 0
	v_mov_b32_e32 v106, 0
	v_mov_b32_e32 v107, 0
	v_mov_b32_e32 v108, 0
	v_mov_b32_e32 v109, 0
	v_mov_b32_e32 v114, 0
	v_mov_b32_e32 v115, 0
	v_mov_b32_e32 v117, 0
	v_mov_b32_e32 v120, 0
	v_mov_b32_e32 v121, 0
	v_mov_b32_e32 v122, 0
	v_mov_b32_e32 v123, 0
	v_mov_b32_e32 v124, 0
	v_mov_b32_e32 v125, 0
	v_mov_b32_e32 v126, 0
	v_mov_b32_e32 v127, 0
	v_mov_b32_e32 v128, 0
	v_mov_b32_e32 v129, 0
	s_cbranch_vccz .LBB0_1106
	s_waitcnt vmcnt(0)
	v_readlane_b32 s12, v255, 32
	v_readlane_b32 s52, v255, 35
	v_readlane_b32 s60, v255, 37
	s_cmpk_gt_u32 s8, 0xff
	v_readlane_b32 s13, v255, 33
	v_readlane_b32 s53, v255, 36
	v_readlane_b32 s61, v255, 38
	s_cbranch_scc1 .LBB0_1113
	s_barrier
